# K=4096 down-projections: each XCD takes its two 8-row-tile groups in reverse order (most recently written hidden activations first)
# baseline (speedup 1.0000x reference)
.LBB0_220:
	s_lshl_b32 s4, s2, 3
	s_abs_i32 s5, s4
	v_cvt_f32_u32_e32 v0, s5
	s_sub_i32 s12, 0, s5
	s_ashr_i32 s3, s3, 3
	s_add_i32 s3, s8, s3
	v_rcp_iflag_f32_e32 v0, v0
	s_abs_i32 s9, s3
	s_xor_b32 s8, s3, s4
	s_ashr_i32 s8, s8, 31
	v_mul_f32_e32 v0, 0x4f7ffffe, v0
	v_cvt_u32_f32_e32 v0, v0
	s_nop 0
	v_readfirstlane_b32 s13, v0
	s_mul_i32 s12, s12, s13
	s_mul_hi_u32 s12, s13, s12
	s_add_i32 s13, s13, s12
	s_mul_hi_u32 s12, s9, s13
	s_mul_i32 s13, s12, s5
	s_sub_i32 s9, s9, s13
	s_add_i32 s18, s12, 1
	s_sub_i32 s13, s9, s5
	s_cmp_ge_u32 s9, s5
	s_cselect_b32 s12, s18, s12
	s_cselect_b32 s9, s13, s9
	s_add_i32 s13, s12, 1
	s_cmp_ge_u32 s9, s5
	s_cselect_b32 s5, s13, s12
	s_xor_b32 s5, s5, s8
	s_sub_i32 s5, s5, s8
	s_lshl_b32 s8, s5, 3
	s_cmp_eq_u32 s35, 0x1000
	s_cselect_b32 vcc_lo, 8, 0
	s_xor_b32 s8, s8, vcc_lo
	s_sub_i32 s9, s73, s8
	s_min_i32 s9, s9, 8
	s_abs_i32 s12, s9
	v_cvt_f32_u32_e32 v0, s12
	s_sub_i32 s13, 0, s12
	s_mul_i32 s5, s5, s4
	s_sub_i32 s3, s3, s5
	v_rcp_iflag_f32_e32 v0, v0
	s_abs_i32 s5, s3
	s_add_i32 s4, s8, s89
	s_xor_b32 s8, s3, s9
	v_mul_f32_e32 v0, 0x4f7ffffe, v0
	v_cvt_u32_f32_e32 v0, v0
	s_ashr_i32 s8, s8, 31
	v_readfirstlane_b32 s18, v0
	s_mul_i32 s13, s13, s18
	s_mul_hi_u32 s13, s18, s13
	s_add_i32 s18, s18, s13
	s_mul_hi_u32 s13, s5, s18
	s_mul_i32 s18, s13, s12
	s_sub_i32 s5, s5, s18
	s_add_i32 s19, s13, 1
	s_sub_i32 s18, s5, s12
	s_cmp_ge_u32 s5, s12
	s_cselect_b32 s13, s19, s13
	s_cselect_b32 s5, s18, s5
	s_add_i32 s18, s13, 1
	s_cmp_ge_u32 s5, s12
	s_cselect_b32 s5, s18, s13
	s_xor_b32 s5, s5, s8
	s_sub_i32 s56, s5, s8
	s_mul_i32 s5, s56, s9
	s_sub_i32 s3, s3, s5
	s_add_i32 s68, s4, s3

.LBB0_241:
	s_ashr_i32 s2, s2, 3
	s_add_i32 s2, s48, s2
	s_abs_i32 s40, s2
	s_mul_hi_u32 s41, s40, s97
	s_mul_i32 s48, s41, s96
	s_ashr_i32 s23, s2, 31
	s_sub_i32 s40, s40, s48
	s_xor_b32 s23, s23, s11
	s_add_i32 s48, s41, 1
	s_sub_i32 s49, s40, s96
	s_cmp_ge_u32 s40, s96
	s_cselect_b32 s41, s48, s41
	s_cselect_b32 s40, s49, s40
	s_add_i32 s48, s41, 1
	s_cmp_ge_u32 s40, s96
	s_cselect_b32 s40, s48, s41
	s_xor_b32 s40, s40, s23
	s_sub_i32 s23, s40, s23
	s_lshl_b32 s40, s23, 3
	s_cmp_eq_u32 s88, 64
	s_cselect_b32 vcc_lo, 8, 0
	s_xor_b32 s40, s40, vcc_lo
	s_sub_i32 s41, s73, s40
	s_min_i32 s41, s41, 8
	s_abs_i32 s48, s41
	v_cvt_f32_u32_e32 v0, s48
	s_sub_i32 s57, 0, s48
	s_mul_i32 s23, s23, s99
	s_sub_i32 s23, s2, s23
	v_rcp_iflag_f32_e32 v0, v0
	s_abs_i32 s49, s23
	s_xor_b32 s2, s23, s41
	s_add_i32 s40, s40, s89
	v_mul_f32_e32 v0, 0x4f7ffffe, v0
	v_cvt_u32_f32_e32 v0, v0
	s_ashr_i32 s2, s2, 31
	v_readfirstlane_b32 s64, v0
	s_mul_i32 s57, s57, s64
	s_mul_hi_u32 s57, s64, s57
	s_add_i32 s64, s64, s57
	s_mul_hi_u32 s57, s49, s64
	s_mul_i32 s64, s57, s48
	s_sub_i32 s49, s49, s64
	s_add_i32 s64, s57, 1
	s_sub_i32 s65, s49, s48
	s_cmp_ge_u32 s49, s48
	s_cselect_b32 s57, s64, s57
	s_cselect_b32 s49, s65, s49
	s_add_i32 s64, s57, 1
	s_cmp_ge_u32 s49, s48
	s_cselect_b32 s48, s64, s57
	s_xor_b32 s48, s48, s2
	s_sub_i32 s2, s48, s2
	s_mul_i32 s41, s2, s41
	s_sub_i32 s23, s23, s41
	s_add_i32 s57, s40, s23
